# QK, Vt and final residual GEMM K-loops: scalar-base LDS-DMA loads and persistent A-fragment LDS base (no VALU in load segments), as already done for Up and the main residual GEMM
# speedup vs baseline: 1.0150x; 1.0047x over previous
; #define PG8_STAGE(bufoff, gbase, voff) do { _Pragma("unroll") for (int _i = 0; _i < 2; ++_i) \
;         __builtin_amdgcn_global_load_lds((const unsigned*)((const char*)(gbase) + (voff)[_i]), (LAS unsigned*)(lds + (bufoff) + ldsw + _i * 8192), 16, 0, 0); } while (0)
; #define PG8_LDA(dst, b, h) do { _Pragma("unroll") for (int m = 0; m < 4; ++m) _Pragma("unroll") for (int k = 0; k < 2; ++k) dst[m][k] = *(const LAS bf16x8*)(lds + PG8_SA(b, h) + aoff + m * 2048 + k * 1024); } while (0)
; #define PG8_LDB(dst, b, h) do { _Pragma("unroll") for (int n = 0; n < 2; ++n) _Pragma("unroll") for (int k = 0; k < 2; ++k) dst[n][k] = *(const LAS bf16x8*)(lds + PG8_SB(b, h) + boff + n * 2048 + k * 1024); } while (0)
; #define PG8_WAIT_V(n) asm volatile("s_waitcnt vmcnt(" #n ")" ::: "memory")
; #define PG8_WAIT_L(n) asm volatile("s_waitcnt lgkmcnt(" #n ")" ::: "memory")
; #define PG8_BAR __builtin_amdgcn_s_barrier()
; template <class Epi, class Sched>
; __device__ __forceinline__ void gemm_phase(LAS unsigned char* lds, const Gemm g, const Sched& S, const Epi& E) {
;     ...
;     for (;;) {
;         const bool has_next = S.next(ui + 1, nxt);
;         const char* nA = has_next ? (const char*)g.A + (size_t)nxt.pm * tstepA + (size_t)nxt.pn * g.a_pn_off * 2 : cA; const char* nB = has_next ? (const char*)g.Bt + (size_t)nxt.pn * tstepB : cB;
;         for (int t = 0; t < nt; t += 2) {
;             const bool last = (t == nt - 2);
;             const char* a1 = cA + (size_t)(t + 1) * kstep;
;             const char* a2 = last ? nA : cA + (size_t)(t + 2) * kstep; const char* b2 = last ? nB : cB + (size_t)(t + 2) * kstep;
;             const char* a3 = a2 + kstep; const char* b3 = b2 + kstep;
;             PG8_LDB(B0, 0, 0); PG8_LDB(B1, 0, 1); PG8_SCHED; PG8_LDA(At, 0, 0); PG8_STAGE(PG8_SA(1, 1), a1 + hstepA, voffA);
;             PG8_WAIT_V(8); PG8_WAIT_L(0); PG8_BAR; PG8_MMA(0, 0, At, B0); PG8_MMA(0, 1, At, B1); PG8_BAR; PG8_SCHED;
;             PG8_LDA(At, 0, 1); PG8_STAGE(PG8_SB(0, 0), b2, voffB); PG8_STAGE(PG8_SB(0, 1), b2 + hstepB, voffB); PG8_STAGE(PG8_SA(0, 0), a2, voffA);
;             PG8_WAIT_V(8); PG8_WAIT_L(0); PG8_BAR; PG8_MMA(1, 0, At, B0); PG8_MMA(1, 1, At, B1); PG8_BAR; PG8_SCHED;
; __device__ __forceinline__ void acc_zero(f32x4 (&acc)[2][2][4][2]) {
;     ...
;                 for (int n = 0; n < 2; ++n) acc[a][b][m][n] = (f32x4){0.f, 0.f, 0.f, 0.f};
.LBB0_348:
	s_ashr_i32 s71, s70, 31
	s_lshl_b64 s[48:49], s[70:71], 19
	s_add_u32 s72, s4, s48
	s_addc_u32 s73, s5, s49
	s_and_b64 s[48:49], s[66:67], exec
	s_cselect_b32 s48, s73, s19
	s_cselect_b32 s49, s72, s18
	s_ashr_i32 s69, s68, 31
	s_lshl_b64 s[74:75], s[68:69], 19
	v_readlane_b32 s12, v248, 13
	s_add_u32 s74, s12, s74
	v_readlane_b32 s12, v248, 14
	s_addc_u32 s75, s12, s75
	s_and_b64 s[76:77], s[66:67], exec
	s_cselect_b32 s53, s75, s21
	s_cselect_b32 s54, s74, s20
	s_add_u32 s18, s18, 0x40080
	s_addc_u32 s19, s19, 0
	s_add_u32 s69, s20, 0x100
	v_mov_b32_e32 v2, 0
	s_addc_u32 s71, s21, 0
	s_mov_b32 s78, -2
	v_mov_b32_e32 v3, v2
	v_mov_b32_e32 v4, v2
	v_mov_b32_e32 v5, v2
	v_mov_b32_e32 v6, v2
	v_mov_b32_e32 v7, v2
	v_mov_b32_e32 v8, v2
	v_mov_b32_e32 v9, v2
	v_mov_b32_e32 v14, v2
	v_mov_b32_e32 v15, v2
	v_mov_b32_e32 v16, v2
	v_mov_b32_e32 v17, v2
	v_mov_b32_e32 v22, v2
	v_mov_b32_e32 v23, v2
	v_mov_b32_e32 v24, v2
	v_mov_b32_e32 v25, v2
	v_mov_b32_e32 v34, v2
	v_mov_b32_e32 v35, v2
	v_mov_b32_e32 v36, v2
	v_mov_b32_e32 v37, v2
	v_mov_b32_e32 v38, v2
	v_mov_b32_e32 v39, v2
	v_mov_b32_e32 v40, v2
	v_mov_b32_e32 v41, v2
	v_mov_b32_e32 v46, v2
	v_mov_b32_e32 v47, v2
	v_mov_b32_e32 v48, v2
	v_mov_b32_e32 v49, v2
	v_mov_b32_e32 v54, v2
	v_mov_b32_e32 v55, v2
	v_mov_b32_e32 v56, v2
	v_mov_b32_e32 v57, v2
	v_mov_b32_e32 v10, v2
	v_mov_b32_e32 v11, v2
	v_mov_b32_e32 v12, v2
	v_mov_b32_e32 v13, v2
	v_mov_b32_e32 v18, v2
	v_mov_b32_e32 v19, v2
	v_mov_b32_e32 v20, v2
	v_mov_b32_e32 v21, v2
	v_mov_b32_e32 v26, v2
	v_mov_b32_e32 v27, v2
	v_mov_b32_e32 v28, v2
	v_mov_b32_e32 v29, v2
	v_mov_b32_e32 v30, v2
	v_mov_b32_e32 v31, v2
	v_mov_b32_e32 v32, v2
	v_mov_b32_e32 v33, v2
	v_mov_b32_e32 v42, v2
	v_mov_b32_e32 v43, v2
	v_mov_b32_e32 v44, v2
	v_mov_b32_e32 v45, v2
	v_mov_b32_e32 v50, v2
	v_mov_b32_e32 v51, v2
	v_mov_b32_e32 v52, v2
	v_mov_b32_e32 v53, v2
	v_mov_b32_e32 v58, v2
	v_mov_b32_e32 v59, v2
	v_mov_b32_e32 v60, v2
	v_mov_b32_e32 v61, v2
	v_mov_b32_e32 v62, v2
	v_mov_b32_e32 v63, v2
	v_mov_b32_e32 v64, v2
	v_mov_b32_e32 v65, v2
	v_mov_b32_e32 v66, v2
	v_mov_b32_e32 v67, v2
	v_mov_b32_e32 v68, v2
	v_mov_b32_e32 v69, v2
	v_mov_b32_e32 v70, v2
	v_mov_b32_e32 v71, v2
	v_mov_b32_e32 v72, v2
	s_waitcnt vmcnt(0)
	v_mov_b32_e32 v73, v2
	v_mov_b32_e32 v78, v2
	v_mov_b32_e32 v79, v2
	v_mov_b32_e32 v80, v2
	v_mov_b32_e32 v81, v2
	v_mov_b32_e32 v86, v2
	v_mov_b32_e32 v87, v2
	v_mov_b32_e32 v88, v2
	v_mov_b32_e32 v89, v2
	v_mov_b32_e32 v98, v2
	v_mov_b32_e32 v99, v2
	v_mov_b32_e32 v100, v2
	v_mov_b32_e32 v101, v2
	v_mov_b32_e32 v102, v2
	v_mov_b32_e32 v103, v2
	v_mov_b32_e32 v104, v2
	v_mov_b32_e32 v105, v2
	v_mov_b32_e32 v114, v2
	v_mov_b32_e32 v115, v2
	v_mov_b32_e32 v116, v2
	v_mov_b32_e32 v117, v2
	v_mov_b32_e32 v118, v2
	v_mov_b32_e32 v119, v2
	v_mov_b32_e32 v120, v2
	v_mov_b32_e32 v121, v2
	v_mov_b32_e32 v74, v2
	v_mov_b32_e32 v75, v2
	v_mov_b32_e32 v76, v2
	v_mov_b32_e32 v77, v2
	v_mov_b32_e32 v82, v2
	v_mov_b32_e32 v83, v2
	v_mov_b32_e32 v84, v2
	v_mov_b32_e32 v85, v2
	v_mov_b32_e32 v90, v2
	v_mov_b32_e32 v91, v2
	v_mov_b32_e32 v92, v2
	v_mov_b32_e32 v93, v2
	v_mov_b32_e32 v94, v2
	v_mov_b32_e32 v95, v2
	v_mov_b32_e32 v96, v2
	v_mov_b32_e32 v97, v2
	v_mov_b32_e32 v106, v2
	v_mov_b32_e32 v107, v2
	v_mov_b32_e32 v108, v2
	v_mov_b32_e32 v109, v2
	v_mov_b32_e32 v110, v2
	v_mov_b32_e32 v111, v2
	v_mov_b32_e32 v112, v2
	v_mov_b32_e32 v113, v2
	v_mov_b32_e32 v122, v2
	v_mov_b32_e32 v123, v2
	v_mov_b32_e32 v124, v2
	v_mov_b32_e32 v125, v2
	v_mov_b32_e32 v126, v2
	v_mov_b32_e32 v127, v2
	v_mov_b32_e32 v128, v2
	v_mov_b32_e32 v129, v2
	v_add_u32_e32 v255, 0x10000, v139
.LBB0_349:
	s_add_u32 s20, s18, 0xfffc0080
	s_addc_u32 s21, s19, -1
	s_add_i32 s79, 0, 0x10000
	s_cmp_eq_u32 s78, 12
	s_cselect_b32 s21, s48, s21
	s_cselect_b32 s20, s49, s20
	s_cselect_b32 s77, s53, s71
	s_cselect_b32 s76, s54, s69
	s_add_u32 s100, s20, 0x80
	s_addc_u32 s101, s21, 0
	s_add_i32 s82, 0, 0x14000
	ds_read_b128 v[150:153], v255
	ds_read_b128 v[154:157], v255 offset:1024
	ds_read_b128 v[158:161], v255 offset:2048
	ds_read_b128 v[162:165], v255 offset:3072
	ds_read_b128 v[166:169], v255 offset:16384
	ds_read_b128 v[170:173], v255 offset:17408
	ds_read_b128 v[190:193], v255 offset:18432
	ds_read_b128 v[194:197], v255 offset:19456
	s_add_i32 m0, s9, 0xc000
	ds_read_b128 v[198:201], v148
	ds_read_b128 v[202:205], v148 offset:1024
	ds_read_b128 v[206:209], v148 offset:2048
	ds_read_b128 v[218:221], v148 offset:3072
	ds_read_b128 v[222:225], v148 offset:4096
	ds_read_b128 v[226:229], v148 offset:5120
	ds_read_b128 v[230:233], v148 offset:6144
	ds_read_b128 v[234:237], v148 offset:7168
	global_load_lds_dwordx4 v130, s[18:19]
	s_add_i32 m0, s9, 0xe000
	s_nop 0
	global_load_lds_dwordx4 v134, s[18:19]
	s_waitcnt vmcnt(8)
	s_waitcnt lgkmcnt(0)
	s_barrier
; #define PG8_STAGE(bufoff, gbase, voff) do { _Pragma("unroll") for (int _i = 0; _i < 2; ++_i) \
;         __builtin_amdgcn_global_load_lds((const unsigned*)((const char*)(gbase) + (voff)[_i]), (LAS unsigned*)(lds + (bufoff) + ldsw + _i * 8192), 16, 0, 0); } while (0)
; #define PG8_LDA(dst, b, h) do { _Pragma("unroll") for (int m = 0; m < 4; ++m) _Pragma("unroll") for (int k = 0; k < 2; ++k) dst[m][k] = *(const LAS bf16x8*)(lds + PG8_SA(b, h) + aoff + m * 2048 + k * 1024); } while (0)
; #define PG8_MMA(ai, bj, At, Bt) do { __builtin_amdgcn_s_setprio(1); _Pragma("unroll") for (int m = 0; m < 4; ++m) _Pragma("unroll") for (int n = 0; n < 2; ++n) _Pragma("unroll") for (int k = 0; k < 2; ++k) \
;         acc[ai][bj][m][n] = __builtin_amdgcn_mfma_f32_16x16x32_bf16(Bt[n][k], At[m][k], acc[ai][bj][m][n], 0, 0, 0); __builtin_amdgcn_s_setprio(0); } while (0)
; #define PG8_WAIT_V(n) asm volatile("s_waitcnt vmcnt(" #n ")" ::: "memory")
; #define PG8_WAIT_L(n) asm volatile("s_waitcnt lgkmcnt(" #n ")" ::: "memory")
; #define PG8_BAR __builtin_amdgcn_s_barrier()
; #define PG8_SCHED __builtin_amdgcn_sched_barrier(0)
; template <class Epi, class Sched>
; __device__ __forceinline__ void gemm_phase(LAS unsigned char* lds, const Gemm g, const Sched& S, const Epi& E) {
;     ...
;             PG8_WAIT_V(8); PG8_WAIT_L(0); PG8_BAR; PG8_MMA(0, 0, At, B0); PG8_MMA(0, 1, At, B1); PG8_BAR; PG8_SCHED;
;             PG8_LDA(At, 0, 1); PG8_STAGE(PG8_SB(0, 0), b2, voffB); PG8_STAGE(PG8_SB(0, 1), b2 + hstepB, voffB); PG8_STAGE(PG8_SA(0, 0), a2, voffA);
;             PG8_WAIT_V(8); PG8_WAIT_L(0); PG8_BAR; PG8_MMA(1, 0, At, B0); PG8_MMA(1, 1, At, B1); PG8_BAR; PG8_SCHED;
	s_setprio 1
	s_waitcnt lgkmcnt(0)
	v_mfma_f32_16x16x32_bf16 v[126:129], v[150:153], v[198:201], v[126:129]
	v_mfma_f32_16x16x32_bf16 v[122:125], v[158:161], v[198:201], v[122:125]
	v_mfma_f32_16x16x32_bf16 v[110:113], v[150:153], v[206:209], v[110:113]
	v_mfma_f32_16x16x32_bf16 v[106:109], v[158:161], v[206:209], v[106:109]
	v_mfma_f32_16x16x32_bf16 v[94:97], v[150:153], v[222:225], v[94:97]
	v_mfma_f32_16x16x32_bf16 v[90:93], v[158:161], v[222:225], v[90:93]
	v_mfma_f32_16x16x32_bf16 v[82:85], v[150:153], v[230:233], v[82:85]
	v_mfma_f32_16x16x32_bf16 v[74:77], v[158:161], v[230:233], v[74:77]
	v_mfma_f32_16x16x32_bf16 v[126:129], v[154:157], v[202:205], v[126:129]
	v_mfma_f32_16x16x32_bf16 v[122:125], v[162:165], v[202:205], v[122:125]
	v_mfma_f32_16x16x32_bf16 v[110:113], v[154:157], v[218:221], v[110:113]
	v_mfma_f32_16x16x32_bf16 v[106:109], v[162:165], v[218:221], v[106:109]
	v_mfma_f32_16x16x32_bf16 v[94:97], v[154:157], v[226:229], v[94:97]
	v_mfma_f32_16x16x32_bf16 v[90:93], v[162:165], v[226:229], v[90:93]
	v_mfma_f32_16x16x32_bf16 v[82:85], v[154:157], v[234:237], v[82:85]
	v_mfma_f32_16x16x32_bf16 v[74:77], v[162:165], v[234:237], v[74:77]
	s_setprio 0
	s_setprio 1
	v_mfma_f32_16x16x32_bf16 v[118:121], v[166:169], v[198:201], v[118:121]
	v_mfma_f32_16x16x32_bf16 v[114:117], v[190:193], v[198:201], v[114:117]
	v_mfma_f32_16x16x32_bf16 v[102:105], v[166:169], v[206:209], v[102:105]
	v_mfma_f32_16x16x32_bf16 v[98:101], v[190:193], v[206:209], v[98:101]
	v_mfma_f32_16x16x32_bf16 v[86:89], v[166:169], v[222:225], v[86:89]
	v_mfma_f32_16x16x32_bf16 v[78:81], v[190:193], v[222:225], v[78:81]
	v_mfma_f32_16x16x32_bf16 v[70:73], v[166:169], v[230:233], v[70:73]
	v_mfma_f32_16x16x32_bf16 v[66:69], v[190:193], v[230:233], v[66:69]
	v_mfma_f32_16x16x32_bf16 v[118:121], v[170:173], v[202:205], v[118:121]
	v_mfma_f32_16x16x32_bf16 v[114:117], v[194:197], v[202:205], v[114:117]
	v_mfma_f32_16x16x32_bf16 v[102:105], v[170:173], v[218:221], v[102:105]
	v_mfma_f32_16x16x32_bf16 v[98:101], v[194:197], v[218:221], v[98:101]
	v_mfma_f32_16x16x32_bf16 v[86:89], v[170:173], v[226:229], v[86:89]
	v_mfma_f32_16x16x32_bf16 v[78:81], v[194:197], v[226:229], v[78:81]
	v_mfma_f32_16x16x32_bf16 v[70:73], v[170:173], v[234:237], v[70:73]
	v_mfma_f32_16x16x32_bf16 v[66:69], v[194:197], v[234:237], v[66:69]
	s_setprio 0
	s_barrier
	s_add_i32 s79, s79, s8
	s_mov_b32 m0, s79
	ds_read_b128 v[198:201], v148 offset:16384
	ds_read_b128 v[202:205], v148 offset:17408
	ds_read_b128 v[206:209], v148 offset:18432
	ds_read_b128 v[218:221], v148 offset:19456
	ds_read_b128 v[222:225], v148 offset:20480
	ds_read_b128 v[226:229], v148 offset:21504
	ds_read_b128 v[230:233], v148 offset:22528
	ds_read_b128 v[234:237], v148 offset:23552
	global_load_lds_dwordx4 v132, s[76:77]
	s_add_i32 m0, s79, 0x2000
	s_add_u32 s80, s76, 0x40000
	s_addc_u32 s81, s77, 0
	s_add_i32 s79, s82, s8
	global_load_lds_dwordx4 v136, s[76:77]
	s_mov_b32 m0, s79
	s_nop 0
	global_load_lds_dwordx4 v132, s[80:81]
	s_add_i32 m0, s79, 0x2000
	s_nop 0
	global_load_lds_dwordx4 v136, s[80:81]
	s_mov_b32 m0, s9
	s_nop 0
	global_load_lds_dwordx4 v130, s[20:21]
	s_mov_b32 m0, s28
	s_nop 0
	global_load_lds_dwordx4 v134, s[20:21]
	s_waitcnt vmcnt(8)
	s_waitcnt lgkmcnt(0)
	s_barrier
	s_setprio 1
	s_waitcnt lgkmcnt(0)
	v_mfma_f32_16x16x32_bf16 v[62:65], v[150:153], v[198:201], v[62:65]
	v_mfma_f32_16x16x32_bf16 v[58:61], v[158:161], v[198:201], v[58:61]
	v_mfma_f32_16x16x32_bf16 v[50:53], v[150:153], v[206:209], v[50:53]
	v_mfma_f32_16x16x32_bf16 v[42:45], v[158:161], v[206:209], v[42:45]
	v_mfma_f32_16x16x32_bf16 v[30:33], v[150:153], v[222:225], v[30:33]
	v_mfma_f32_16x16x32_bf16 v[26:29], v[158:161], v[222:225], v[26:29]
	v_mfma_f32_16x16x32_bf16 v[18:21], v[150:153], v[230:233], v[18:21]
	v_mfma_f32_16x16x32_bf16 v[10:13], v[158:161], v[230:233], v[10:13]
	v_mfma_f32_16x16x32_bf16 v[62:65], v[154:157], v[202:205], v[62:65]
	v_mfma_f32_16x16x32_bf16 v[58:61], v[162:165], v[202:205], v[58:61]
	v_mfma_f32_16x16x32_bf16 v[50:53], v[154:157], v[218:221], v[50:53]
	v_mfma_f32_16x16x32_bf16 v[42:45], v[162:165], v[218:221], v[42:45]
	v_mfma_f32_16x16x32_bf16 v[30:33], v[154:157], v[226:229], v[30:33]
	v_mfma_f32_16x16x32_bf16 v[26:29], v[162:165], v[226:229], v[26:29]
	v_mfma_f32_16x16x32_bf16 v[18:21], v[154:157], v[234:237], v[18:21]
	v_mfma_f32_16x16x32_bf16 v[10:13], v[162:165], v[234:237], v[10:13]
	s_setprio 0
	s_setprio 1
	v_mfma_f32_16x16x32_bf16 v[54:57], v[166:169], v[198:201], v[54:57]
	v_mfma_f32_16x16x32_bf16 v[46:49], v[190:193], v[198:201], v[46:49]
	v_mfma_f32_16x16x32_bf16 v[38:41], v[166:169], v[206:209], v[38:41]
	v_mfma_f32_16x16x32_bf16 v[34:37], v[190:193], v[206:209], v[34:37]
	v_mfma_f32_16x16x32_bf16 v[22:25], v[166:169], v[222:225], v[22:25]
	v_mfma_f32_16x16x32_bf16 v[14:17], v[190:193], v[222:225], v[14:17]
	v_mfma_f32_16x16x32_bf16 v[6:9], v[166:169], v[230:233], v[6:9]
	v_mfma_f32_16x16x32_bf16 v[2:5], v[190:193], v[230:233], v[2:5]
	v_mfma_f32_16x16x32_bf16 v[54:57], v[170:173], v[202:205], v[54:57]
	v_mfma_f32_16x16x32_bf16 v[46:49], v[194:197], v[202:205], v[46:49]
	v_mfma_f32_16x16x32_bf16 v[38:41], v[170:173], v[218:221], v[38:41]
	v_mfma_f32_16x16x32_bf16 v[34:37], v[194:197], v[218:221], v[34:37]
	v_mfma_f32_16x16x32_bf16 v[22:25], v[170:173], v[226:229], v[22:25]
	v_mfma_f32_16x16x32_bf16 v[14:17], v[194:197], v[226:229], v[14:17]
	v_mfma_f32_16x16x32_bf16 v[6:9], v[170:173], v[234:237], v[6:9]
	v_mfma_f32_16x16x32_bf16 v[2:5], v[194:197], v[234:237], v[2:5]
	s_setprio 0
	s_barrier
; #define PG8_STAGE(bufoff, gbase, voff) do { _Pragma("unroll") for (int _i = 0; _i < 2; ++_i) \
;         __builtin_amdgcn_global_load_lds((const unsigned*)((const char*)(gbase) + (voff)[_i]), (LAS unsigned*)(lds + (bufoff) + ldsw + _i * 8192), 16, 0, 0); } while (0)
; #define PG8_LDA(dst, b, h) do { _Pragma("unroll") for (int m = 0; m < 4; ++m) _Pragma("unroll") for (int k = 0; k < 2; ++k) dst[m][k] = *(const LAS bf16x8*)(lds + PG8_SA(b, h) + aoff + m * 2048 + k * 1024); } while (0)
; #define PG8_LDB(dst, b, h) do { _Pragma("unroll") for (int n = 0; n < 2; ++n) _Pragma("unroll") for (int k = 0; k < 2; ++k) dst[n][k] = *(const LAS bf16x8*)(lds + PG8_SB(b, h) + boff + n * 2048 + k * 1024); } while (0)
; #define PG8_MMA(ai, bj, At, Bt) do { __builtin_amdgcn_s_setprio(1); _Pragma("unroll") for (int m = 0; m < 4; ++m) _Pragma("unroll") for (int n = 0; n < 2; ++n) _Pragma("unroll") for (int k = 0; k < 2; ++k) \
;         acc[ai][bj][m][n] = __builtin_amdgcn_mfma_f32_16x16x32_bf16(Bt[n][k], At[m][k], acc[ai][bj][m][n], 0, 0, 0); __builtin_amdgcn_s_setprio(0); } while (0)
; #define PG8_WAIT_V(n) asm volatile("s_waitcnt vmcnt(" #n ")" ::: "memory")
; #define PG8_WAIT_L(n) asm volatile("s_waitcnt lgkmcnt(" #n ")" ::: "memory")
; #define PG8_BAR __builtin_amdgcn_s_barrier()
; #define PG8_SCHED __builtin_amdgcn_sched_barrier(0)
; template <class Epi, class Sched>
; __device__ __forceinline__ void gemm_phase(LAS unsigned char* lds, const Gemm g, const Sched& S, const Epi& E) {
;     ...
;             PG8_LDB(B0, 1, 0); PG8_LDB(B1, 1, 1); PG8_SCHED; PG8_LDA(At, 1, 0); PG8_STAGE(PG8_SA(0, 1), a2 + hstepA, voffA);
;             PG8_WAIT_V(8); PG8_WAIT_L(0); PG8_BAR; PG8_MMA(0, 0, At, B0); PG8_MMA(0, 1, At, B1); PG8_BAR; PG8_SCHED;
;             PG8_LDA(At, 1, 1); PG8_STAGE(PG8_SB(1, 0), b3, voffB); PG8_STAGE(PG8_SB(1, 1), b3 + hstepB, voffB); PG8_STAGE(PG8_SA(1, 0), a3, voffA);
;             PG8_WAIT_V(8); PG8_WAIT_L(0); PG8_BAR; PG8_MMA(1, 0, At, B0); PG8_MMA(1, 1, At, B1); PG8_BAR; PG8_SCHED;
;         }
	s_add_i32 s79, 0, 0x18000
	s_add_i32 s80, 0, 0x1c000
	ds_read_b128 v[150:153], v255 offset:32768
	ds_read_b128 v[154:157], v255 offset:33792
	ds_read_b128 v[158:161], v255 offset:34816
	ds_read_b128 v[162:165], v255 offset:35840
	ds_read_b128 v[166:169], v255 offset:49152
	ds_read_b128 v[170:173], v255 offset:50176
	ds_read_b128 v[190:193], v255 offset:51200
	ds_read_b128 v[194:197], v255 offset:52224
	s_add_u32 s20, s20, 0x40000
	s_addc_u32 s21, s21, 0
	s_mov_b32 m0, s29
	ds_read_b128 v[198:201], v148 offset:32768
	ds_read_b128 v[202:205], v148 offset:33792
	ds_read_b128 v[206:209], v148 offset:34816
	ds_read_b128 v[218:221], v148 offset:35840
	ds_read_b128 v[222:225], v148 offset:36864
	ds_read_b128 v[226:229], v148 offset:37888
	ds_read_b128 v[230:233], v148 offset:38912
	ds_read_b128 v[234:237], v148 offset:39936
	global_load_lds_dwordx4 v130, s[20:21]
	s_mov_b32 m0, s30
	s_nop 0
	global_load_lds_dwordx4 v134, s[20:21]
	s_waitcnt vmcnt(8)
	s_waitcnt lgkmcnt(0)
	s_barrier
	s_setprio 1
	s_waitcnt lgkmcnt(0)
	v_mfma_f32_16x16x32_bf16 v[126:129], v[150:153], v[198:201], v[126:129]
	v_mfma_f32_16x16x32_bf16 v[122:125], v[158:161], v[198:201], v[122:125]
	v_mfma_f32_16x16x32_bf16 v[110:113], v[150:153], v[206:209], v[110:113]
	v_mfma_f32_16x16x32_bf16 v[106:109], v[158:161], v[206:209], v[106:109]
	v_mfma_f32_16x16x32_bf16 v[94:97], v[150:153], v[222:225], v[94:97]
	v_mfma_f32_16x16x32_bf16 v[90:93], v[158:161], v[222:225], v[90:93]
	v_mfma_f32_16x16x32_bf16 v[82:85], v[150:153], v[230:233], v[82:85]
	v_mfma_f32_16x16x32_bf16 v[74:77], v[158:161], v[230:233], v[74:77]
	v_mfma_f32_16x16x32_bf16 v[126:129], v[154:157], v[202:205], v[126:129]
	v_mfma_f32_16x16x32_bf16 v[122:125], v[162:165], v[202:205], v[122:125]
	v_mfma_f32_16x16x32_bf16 v[110:113], v[154:157], v[218:221], v[110:113]
	v_mfma_f32_16x16x32_bf16 v[106:109], v[162:165], v[218:221], v[106:109]
	v_mfma_f32_16x16x32_bf16 v[94:97], v[154:157], v[226:229], v[94:97]
	v_mfma_f32_16x16x32_bf16 v[90:93], v[162:165], v[226:229], v[90:93]
	v_mfma_f32_16x16x32_bf16 v[82:85], v[154:157], v[234:237], v[82:85]
	v_mfma_f32_16x16x32_bf16 v[74:77], v[162:165], v[234:237], v[74:77]
	s_setprio 0
	s_setprio 1
	v_mfma_f32_16x16x32_bf16 v[118:121], v[166:169], v[198:201], v[118:121]
	v_mfma_f32_16x16x32_bf16 v[114:117], v[190:193], v[198:201], v[114:117]
	v_mfma_f32_16x16x32_bf16 v[102:105], v[166:169], v[206:209], v[102:105]
	v_mfma_f32_16x16x32_bf16 v[98:101], v[190:193], v[206:209], v[98:101]
	v_mfma_f32_16x16x32_bf16 v[86:89], v[166:169], v[222:225], v[86:89]
	v_mfma_f32_16x16x32_bf16 v[78:81], v[190:193], v[222:225], v[78:81]
	v_mfma_f32_16x16x32_bf16 v[70:73], v[166:169], v[230:233], v[70:73]
	v_mfma_f32_16x16x32_bf16 v[66:69], v[190:193], v[230:233], v[66:69]
	v_mfma_f32_16x16x32_bf16 v[118:121], v[170:173], v[202:205], v[118:121]
	v_mfma_f32_16x16x32_bf16 v[114:117], v[194:197], v[202:205], v[114:117]
	v_mfma_f32_16x16x32_bf16 v[102:105], v[170:173], v[218:221], v[102:105]
	v_mfma_f32_16x16x32_bf16 v[98:101], v[194:197], v[218:221], v[98:101]
	v_mfma_f32_16x16x32_bf16 v[86:89], v[170:173], v[226:229], v[86:89]
	v_mfma_f32_16x16x32_bf16 v[78:81], v[194:197], v[226:229], v[78:81]
	v_mfma_f32_16x16x32_bf16 v[70:73], v[170:173], v[234:237], v[70:73]
	v_mfma_f32_16x16x32_bf16 v[66:69], v[194:197], v[234:237], v[66:69]
	s_setprio 0
	s_barrier
	s_add_i32 s20, s8, 0x18000
	s_add_u32 s80, s76, 0x80
	s_addc_u32 s81, s77, 0
	s_mov_b32 m0, s20
	ds_read_b128 v[198:201], v148 offset:49152
	ds_read_b128 v[202:205], v148 offset:50176
	ds_read_b128 v[206:209], v148 offset:51200
	ds_read_b128 v[218:221], v148 offset:52224
	ds_read_b128 v[222:225], v148 offset:53248
	ds_read_b128 v[226:229], v148 offset:54272
	ds_read_b128 v[230:233], v148 offset:55296
	ds_read_b128 v[234:237], v148 offset:56320
	global_load_lds_dwordx4 v132, s[80:81]
	s_add_i32 m0, s20, 0x2000
	s_add_u32 s20, s76, 0x40080
	s_addc_u32 s21, s77, 0
	s_add_i32 s12, s8, 0x1c000
	global_load_lds_dwordx4 v136, s[80:81]
	s_mov_b32 m0, s12
	s_nop 0
	global_load_lds_dwordx4 v132, s[20:21]
	s_add_i32 m0, s12, 0x2000
	s_nop 0
	global_load_lds_dwordx4 v136, s[20:21]
	s_mov_b32 m0, s31
	s_nop 0
	global_load_lds_dwordx4 v130, s[100:101]
	s_mov_b32 m0, s34
	s_nop 0
	global_load_lds_dwordx4 v134, s[100:101]
	s_waitcnt vmcnt(8)
	s_waitcnt lgkmcnt(0)
	s_barrier
	s_setprio 1
	s_waitcnt lgkmcnt(0)
	v_mfma_f32_16x16x32_bf16 v[62:65], v[150:153], v[198:201], v[62:65]
	v_mfma_f32_16x16x32_bf16 v[58:61], v[158:161], v[198:201], v[58:61]
	v_mfma_f32_16x16x32_bf16 v[50:53], v[150:153], v[206:209], v[50:53]
	v_mfma_f32_16x16x32_bf16 v[42:45], v[158:161], v[206:209], v[42:45]
	v_mfma_f32_16x16x32_bf16 v[30:33], v[150:153], v[222:225], v[30:33]
	v_mfma_f32_16x16x32_bf16 v[26:29], v[158:161], v[222:225], v[26:29]
	v_mfma_f32_16x16x32_bf16 v[18:21], v[150:153], v[230:233], v[18:21]
	v_mfma_f32_16x16x32_bf16 v[10:13], v[158:161], v[230:233], v[10:13]
	v_mfma_f32_16x16x32_bf16 v[62:65], v[154:157], v[202:205], v[62:65]
	v_mfma_f32_16x16x32_bf16 v[58:61], v[162:165], v[202:205], v[58:61]
	v_mfma_f32_16x16x32_bf16 v[50:53], v[154:157], v[218:221], v[50:53]
	v_mfma_f32_16x16x32_bf16 v[42:45], v[162:165], v[218:221], v[42:45]
	v_mfma_f32_16x16x32_bf16 v[30:33], v[154:157], v[226:229], v[30:33]
	v_mfma_f32_16x16x32_bf16 v[26:29], v[162:165], v[226:229], v[26:29]
	v_mfma_f32_16x16x32_bf16 v[18:21], v[154:157], v[234:237], v[18:21]
	v_mfma_f32_16x16x32_bf16 v[10:13], v[162:165], v[234:237], v[10:13]
	s_setprio 0
	s_setprio 1
	v_mfma_f32_16x16x32_bf16 v[54:57], v[166:169], v[198:201], v[54:57]
	v_mfma_f32_16x16x32_bf16 v[46:49], v[190:193], v[198:201], v[46:49]
	v_mfma_f32_16x16x32_bf16 v[38:41], v[166:169], v[206:209], v[38:41]
	v_mfma_f32_16x16x32_bf16 v[34:37], v[190:193], v[206:209], v[34:37]
	v_mfma_f32_16x16x32_bf16 v[22:25], v[166:169], v[222:225], v[22:25]
	v_mfma_f32_16x16x32_bf16 v[14:17], v[190:193], v[222:225], v[14:17]
	v_mfma_f32_16x16x32_bf16 v[6:9], v[166:169], v[230:233], v[6:9]
	v_mfma_f32_16x16x32_bf16 v[2:5], v[190:193], v[230:233], v[2:5]
	v_mfma_f32_16x16x32_bf16 v[54:57], v[170:173], v[202:205], v[54:57]
	v_mfma_f32_16x16x32_bf16 v[46:49], v[194:197], v[202:205], v[46:49]
	v_mfma_f32_16x16x32_bf16 v[38:41], v[170:173], v[218:221], v[38:41]
	v_mfma_f32_16x16x32_bf16 v[34:37], v[194:197], v[218:221], v[34:37]
	v_mfma_f32_16x16x32_bf16 v[22:25], v[170:173], v[226:229], v[22:25]
	v_mfma_f32_16x16x32_bf16 v[14:17], v[194:197], v[226:229], v[14:17]
	v_mfma_f32_16x16x32_bf16 v[6:9], v[170:173], v[234:237], v[6:9]
	v_mfma_f32_16x16x32_bf16 v[2:5], v[194:197], v[234:237], v[2:5]
	s_setprio 0
	s_barrier
	s_add_i32 s78, s78, 2
	s_add_u32 s18, s18, 0x100
	s_addc_u32 s19, s19, 0
	s_add_u32 s69, s69, 0x100
	s_addc_u32 s71, s71, 0
	s_cmp_gt_u32 s78, 13
	s_cbranch_scc0 .LBB0_349
	s_and_b64 vcc, exec, s[36:37]
	s_cbranch_vccz .LBB0_352
	s_barrier

; template <class Epi, class Sched>
; __device__ __forceinline__ void gemm_phase(LAS unsigned char* lds, const Gemm g, const Sched& S, const Epi& E) {
;     ...
;     for (;;) {
;         const bool has_next = S.next(ui + 1, nxt);
;         const char* nA = has_next ? (const char*)g.A + (size_t)nxt.pm * tstepA + (size_t)nxt.pn * g.a_pn_off * 2 : cA; const char* nB = has_next ? (const char*)g.Bt + (size_t)nxt.pn * tstepB : cB;
; __device__ __forceinline__ void acc_zero(f32x4 (&acc)[2][2][4][2]) {
;     ...
;                 for (int n = 0; n < 2; ++n) acc[a][b][m][n] = (f32x4){0.f, 0.f, 0.f, 0.f};
.LBB0_377:
	s_ashr_i32 s71, s70, 31
	s_lshl_b64 s[48:49], s[70:71], 19
	v_readlane_b32 s12, v248, 21
	s_add_u32 s72, s12, s48
	v_readlane_b32 s12, v248, 22
	s_addc_u32 s73, s12, s49
	s_and_b64 s[48:49], s[66:67], exec
	s_cselect_b32 s43, s73, s19
	s_cselect_b32 s48, s72, s18
	s_ashr_i32 s69, s68, 31
	s_lshl_b64 s[74:75], s[68:69], 19
	s_add_u32 s74, s4, s74
	s_addc_u32 s75, s5, s75
	s_and_b64 s[76:77], s[66:67], exec
	s_cselect_b32 s49, s75, s21
	s_cselect_b32 s53, s74, s20
	s_add_u32 s18, s18, 0x40080
	s_addc_u32 s19, s19, 0
	s_add_u32 s69, s20, 0x100
	v_mov_b32_e32 v2, 0
	s_addc_u32 s71, s21, 0
	s_mov_b32 s78, -2
	v_mov_b32_e32 v3, v2
	v_mov_b32_e32 v4, v2
	v_mov_b32_e32 v5, v2
	v_mov_b32_e32 v6, v2
	v_mov_b32_e32 v7, v2
	v_mov_b32_e32 v8, v2
	v_mov_b32_e32 v9, v2
	v_mov_b32_e32 v10, v2
	v_mov_b32_e32 v11, v2
	v_mov_b32_e32 v12, v2
	v_mov_b32_e32 v13, v2
	v_mov_b32_e32 v18, v2
	v_mov_b32_e32 v19, v2
	v_mov_b32_e32 v20, v2
	v_mov_b32_e32 v21, v2
	v_mov_b32_e32 v26, v2
	v_mov_b32_e32 v27, v2
	v_mov_b32_e32 v28, v2
	v_mov_b32_e32 v29, v2
	v_mov_b32_e32 v34, v2
	v_mov_b32_e32 v35, v2
	v_mov_b32_e32 v36, v2
	v_mov_b32_e32 v37, v2
	v_mov_b32_e32 v42, v2
	v_mov_b32_e32 v43, v2
	v_mov_b32_e32 v44, v2
	v_mov_b32_e32 v45, v2
	v_mov_b32_e32 v50, v2
	v_mov_b32_e32 v51, v2
	v_mov_b32_e32 v52, v2
	v_mov_b32_e32 v53, v2
	v_mov_b32_e32 v14, v2
	v_mov_b32_e32 v15, v2
	v_mov_b32_e32 v16, v2
	v_mov_b32_e32 v17, v2
	v_mov_b32_e32 v22, v2
	v_mov_b32_e32 v23, v2
	v_mov_b32_e32 v24, v2
	v_mov_b32_e32 v25, v2
	v_mov_b32_e32 v30, v2
	v_mov_b32_e32 v31, v2
	v_mov_b32_e32 v32, v2
	v_mov_b32_e32 v33, v2
	v_mov_b32_e32 v38, v2
	v_mov_b32_e32 v39, v2
	v_mov_b32_e32 v40, v2
	v_mov_b32_e32 v41, v2
	v_mov_b32_e32 v46, v2
	v_mov_b32_e32 v47, v2
	v_mov_b32_e32 v48, v2
	v_mov_b32_e32 v49, v2
	v_mov_b32_e32 v54, v2
	v_mov_b32_e32 v55, v2
	v_mov_b32_e32 v56, v2
	v_mov_b32_e32 v57, v2
	v_mov_b32_e32 v58, v2
	v_mov_b32_e32 v59, v2
	v_mov_b32_e32 v60, v2
	v_mov_b32_e32 v61, v2
	v_mov_b32_e32 v62, v2
	v_mov_b32_e32 v63, v2
	v_mov_b32_e32 v64, v2
	v_mov_b32_e32 v65, v2
	v_mov_b32_e32 v66, v2
	v_mov_b32_e32 v67, v2
	v_mov_b32_e32 v68, v2
	v_mov_b32_e32 v69, v2
	v_mov_b32_e32 v70, v2
	v_mov_b32_e32 v71, v2
	v_mov_b32_e32 v72, v2
	v_mov_b32_e32 v73, v2
	v_mov_b32_e32 v74, v2
	v_mov_b32_e32 v75, v2
	v_mov_b32_e32 v76, v2
	v_mov_b32_e32 v77, v2
	v_mov_b32_e32 v82, v2
	v_mov_b32_e32 v83, v2
	v_mov_b32_e32 v84, v2
	v_mov_b32_e32 v85, v2
	v_mov_b32_e32 v90, v2
	v_mov_b32_e32 v91, v2
	v_mov_b32_e32 v92, v2
	v_mov_b32_e32 v93, v2
	v_mov_b32_e32 v98, v2
	v_mov_b32_e32 v99, v2
	v_mov_b32_e32 v100, v2
	v_mov_b32_e32 v101, v2
	v_mov_b32_e32 v106, v2
	v_mov_b32_e32 v107, v2
	v_mov_b32_e32 v108, v2
	v_mov_b32_e32 v109, v2
	v_mov_b32_e32 v114, v2
	v_mov_b32_e32 v115, v2
	v_mov_b32_e32 v116, v2
	v_mov_b32_e32 v117, v2
	v_mov_b32_e32 v78, v2
	v_mov_b32_e32 v79, v2
	v_mov_b32_e32 v80, v2
	v_mov_b32_e32 v81, v2
	v_mov_b32_e32 v86, v2
	v_mov_b32_e32 v87, v2
	v_mov_b32_e32 v88, v2
	v_mov_b32_e32 v89, v2
	v_mov_b32_e32 v94, v2
	v_mov_b32_e32 v95, v2
	v_mov_b32_e32 v96, v2
	v_mov_b32_e32 v97, v2
	v_mov_b32_e32 v102, v2
	v_mov_b32_e32 v103, v2
	v_mov_b32_e32 v104, v2
	v_mov_b32_e32 v105, v2
	v_mov_b32_e32 v110, v2
	v_mov_b32_e32 v111, v2
	v_mov_b32_e32 v112, v2
	v_mov_b32_e32 v113, v2
	v_mov_b32_e32 v118, v2
	v_mov_b32_e32 v119, v2
	v_mov_b32_e32 v120, v2
	v_mov_b32_e32 v121, v2
	v_mov_b32_e32 v122, v2
	v_mov_b32_e32 v123, v2
	v_mov_b32_e32 v124, v2
	v_mov_b32_e32 v125, v2
	v_mov_b32_e32 v126, v2
	v_mov_b32_e32 v127, v2
	v_mov_b32_e32 v128, v2
	v_mov_b32_e32 v129, v2
	v_add_u32_e32 v255, 0x10000, v158
.LBB0_378:
	s_add_u32 s20, s18, 0xfffc0080
	s_addc_u32 s21, s19, -1
	s_add_i32 s79, 0, 0x10000
	s_cmp_eq_u32 s78, 12
	s_cselect_b32 s21, s43, s21
	s_cselect_b32 s20, s48, s20
	s_cselect_b32 s77, s49, s71
	s_cselect_b32 s76, s53, s69
	s_add_u32 s100, s20, 0x80
	s_addc_u32 s101, s21, 0
	s_add_i32 s82, 0, 0x14000
	ds_read_b128 v[130:133], v255
	ds_read_b128 v[134:137], v255 offset:1024
	ds_read_b128 v[138:141], v255 offset:2048
	ds_read_b128 v[142:145], v255 offset:3072
	ds_read_b128 v[162:165], v255 offset:16384
	ds_read_b128 v[166:169], v255 offset:17408
	ds_read_b128 v[170:173], v255 offset:18432
	ds_read_b128 v[190:193], v255 offset:19456
	s_add_i32 m0, s9, 0xc000
	ds_read_b128 v[194:197], v160
	ds_read_b128 v[198:201], v160 offset:1024
	ds_read_b128 v[202:205], v160 offset:2048
	ds_read_b128 v[206:209], v160 offset:3072
	ds_read_b128 v[218:221], v160 offset:4096
	ds_read_b128 v[222:225], v160 offset:5120
	ds_read_b128 v[226:229], v160 offset:6144
	ds_read_b128 v[230:233], v160 offset:7168
	global_load_lds_dwordx4 v146, s[18:19]
	s_add_i32 m0, s9, 0xe000
	s_nop 0
	global_load_lds_dwordx4 v150, s[18:19]
	s_waitcnt vmcnt(8)
	s_waitcnt lgkmcnt(0)
	s_barrier
; #define PG8_STAGE(bufoff, gbase, voff) do { _Pragma("unroll") for (int _i = 0; _i < 2; ++_i) \
;         __builtin_amdgcn_global_load_lds((const unsigned*)((const char*)(gbase) + (voff)[_i]), (LAS unsigned*)(lds + (bufoff) + ldsw + _i * 8192), 16, 0, 0); } while (0)
; #define PG8_LDA(dst, b, h) do { _Pragma("unroll") for (int m = 0; m < 4; ++m) _Pragma("unroll") for (int k = 0; k < 2; ++k) dst[m][k] = *(const LAS bf16x8*)(lds + PG8_SA(b, h) + aoff + m * 2048 + k * 1024); } while (0)
; #define PG8_MMA(ai, bj, At, Bt) do { __builtin_amdgcn_s_setprio(1); _Pragma("unroll") for (int m = 0; m < 4; ++m) _Pragma("unroll") for (int n = 0; n < 2; ++n) _Pragma("unroll") for (int k = 0; k < 2; ++k) \
;         acc[ai][bj][m][n] = __builtin_amdgcn_mfma_f32_16x16x32_bf16(Bt[n][k], At[m][k], acc[ai][bj][m][n], 0, 0, 0); __builtin_amdgcn_s_setprio(0); } while (0)
; #define PG8_WAIT_V(n) asm volatile("s_waitcnt vmcnt(" #n ")" ::: "memory")
; #define PG8_WAIT_L(n) asm volatile("s_waitcnt lgkmcnt(" #n ")" ::: "memory")
; #define PG8_BAR __builtin_amdgcn_s_barrier()
; #define PG8_SCHED __builtin_amdgcn_sched_barrier(0)
; template <class Epi, class Sched>
; __device__ __forceinline__ void gemm_phase(LAS unsigned char* lds, const Gemm g, const Sched& S, const Epi& E) {
;     ...
;             PG8_WAIT_V(8); PG8_WAIT_L(0); PG8_BAR; PG8_MMA(0, 0, At, B0); PG8_MMA(0, 1, At, B1); PG8_BAR; PG8_SCHED;
;             PG8_LDA(At, 0, 1); PG8_STAGE(PG8_SB(0, 0), b2, voffB); PG8_STAGE(PG8_SB(0, 1), b2 + hstepB, voffB); PG8_STAGE(PG8_SA(0, 0), a2, voffA);
;             PG8_WAIT_V(8); PG8_WAIT_L(0); PG8_BAR; PG8_MMA(1, 0, At, B0); PG8_MMA(1, 1, At, B1); PG8_BAR; PG8_SCHED;
	s_setprio 1
	s_waitcnt lgkmcnt(0)
	v_mfma_f32_16x16x32_bf16 v[126:129], v[130:133], v[194:197], v[126:129]
	v_mfma_f32_16x16x32_bf16 v[122:125], v[138:141], v[194:197], v[122:125]
	v_mfma_f32_16x16x32_bf16 v[118:121], v[130:133], v[202:205], v[118:121]
	v_mfma_f32_16x16x32_bf16 v[110:113], v[138:141], v[202:205], v[110:113]
	v_mfma_f32_16x16x32_bf16 v[102:105], v[130:133], v[218:221], v[102:105]
	v_mfma_f32_16x16x32_bf16 v[94:97], v[138:141], v[218:221], v[94:97]
	v_mfma_f32_16x16x32_bf16 v[86:89], v[130:133], v[226:229], v[86:89]
	v_mfma_f32_16x16x32_bf16 v[78:81], v[138:141], v[226:229], v[78:81]
	v_mfma_f32_16x16x32_bf16 v[126:129], v[134:137], v[198:201], v[126:129]
	v_mfma_f32_16x16x32_bf16 v[122:125], v[142:145], v[198:201], v[122:125]
	v_mfma_f32_16x16x32_bf16 v[118:121], v[134:137], v[206:209], v[118:121]
	v_mfma_f32_16x16x32_bf16 v[110:113], v[142:145], v[206:209], v[110:113]
	v_mfma_f32_16x16x32_bf16 v[102:105], v[134:137], v[222:225], v[102:105]
	v_mfma_f32_16x16x32_bf16 v[94:97], v[142:145], v[222:225], v[94:97]
	v_mfma_f32_16x16x32_bf16 v[86:89], v[134:137], v[230:233], v[86:89]
	v_mfma_f32_16x16x32_bf16 v[78:81], v[142:145], v[230:233], v[78:81]
	s_setprio 0
	s_setprio 1
	v_mfma_f32_16x16x32_bf16 v[114:117], v[162:165], v[194:197], v[114:117]
	v_mfma_f32_16x16x32_bf16 v[106:109], v[170:173], v[194:197], v[106:109]
	v_mfma_f32_16x16x32_bf16 v[98:101], v[162:165], v[202:205], v[98:101]
	v_mfma_f32_16x16x32_bf16 v[90:93], v[170:173], v[202:205], v[90:93]
	v_mfma_f32_16x16x32_bf16 v[82:85], v[162:165], v[218:221], v[82:85]
	v_mfma_f32_16x16x32_bf16 v[74:77], v[170:173], v[218:221], v[74:77]
	v_mfma_f32_16x16x32_bf16 v[70:73], v[162:165], v[226:229], v[70:73]
	v_mfma_f32_16x16x32_bf16 v[66:69], v[170:173], v[226:229], v[66:69]
	v_mfma_f32_16x16x32_bf16 v[114:117], v[166:169], v[198:201], v[114:117]
	v_mfma_f32_16x16x32_bf16 v[106:109], v[190:193], v[198:201], v[106:109]
	v_mfma_f32_16x16x32_bf16 v[98:101], v[166:169], v[206:209], v[98:101]
	v_mfma_f32_16x16x32_bf16 v[90:93], v[190:193], v[206:209], v[90:93]
	v_mfma_f32_16x16x32_bf16 v[82:85], v[166:169], v[222:225], v[82:85]
	v_mfma_f32_16x16x32_bf16 v[74:77], v[190:193], v[222:225], v[74:77]
	v_mfma_f32_16x16x32_bf16 v[70:73], v[166:169], v[230:233], v[70:73]
	v_mfma_f32_16x16x32_bf16 v[66:69], v[190:193], v[230:233], v[66:69]
	s_setprio 0
	s_barrier
	s_add_i32 s79, s79, s8
	s_mov_b32 m0, s79
	ds_read_b128 v[194:197], v160 offset:16384
	ds_read_b128 v[198:201], v160 offset:17408
	ds_read_b128 v[202:205], v160 offset:18432
	ds_read_b128 v[206:209], v160 offset:19456
	ds_read_b128 v[218:221], v160 offset:20480
	ds_read_b128 v[222:225], v160 offset:21504
	ds_read_b128 v[226:229], v160 offset:22528
	ds_read_b128 v[230:233], v160 offset:23552
	global_load_lds_dwordx4 v148, s[76:77]
	s_add_i32 m0, s79, 0x2000
	s_add_u32 s80, s76, 0x40000
	s_addc_u32 s81, s77, 0
	s_add_i32 s79, s82, s8
	global_load_lds_dwordx4 v152, s[76:77]
	s_mov_b32 m0, s79
	s_nop 0
	global_load_lds_dwordx4 v148, s[80:81]
	s_add_i32 m0, s79, 0x2000
	s_nop 0
	global_load_lds_dwordx4 v152, s[80:81]
	s_mov_b32 m0, s9
	s_nop 0
	global_load_lds_dwordx4 v146, s[20:21]
	s_mov_b32 m0, s28
	s_nop 0
	global_load_lds_dwordx4 v150, s[20:21]
	s_waitcnt vmcnt(8)
	s_waitcnt lgkmcnt(0)
	s_barrier
	s_setprio 1
	s_waitcnt lgkmcnt(0)
	v_mfma_f32_16x16x32_bf16 v[62:65], v[130:133], v[194:197], v[62:65]
	v_mfma_f32_16x16x32_bf16 v[58:61], v[138:141], v[194:197], v[58:61]
	v_mfma_f32_16x16x32_bf16 v[54:57], v[130:133], v[202:205], v[54:57]
	v_mfma_f32_16x16x32_bf16 v[46:49], v[138:141], v[202:205], v[46:49]
	v_mfma_f32_16x16x32_bf16 v[38:41], v[130:133], v[218:221], v[38:41]
	v_mfma_f32_16x16x32_bf16 v[30:33], v[138:141], v[218:221], v[30:33]
	v_mfma_f32_16x16x32_bf16 v[22:25], v[130:133], v[226:229], v[22:25]
	v_mfma_f32_16x16x32_bf16 v[14:17], v[138:141], v[226:229], v[14:17]
	v_mfma_f32_16x16x32_bf16 v[62:65], v[134:137], v[198:201], v[62:65]
	v_mfma_f32_16x16x32_bf16 v[58:61], v[142:145], v[198:201], v[58:61]
	v_mfma_f32_16x16x32_bf16 v[54:57], v[134:137], v[206:209], v[54:57]
	v_mfma_f32_16x16x32_bf16 v[46:49], v[142:145], v[206:209], v[46:49]
	v_mfma_f32_16x16x32_bf16 v[38:41], v[134:137], v[222:225], v[38:41]
	v_mfma_f32_16x16x32_bf16 v[30:33], v[142:145], v[222:225], v[30:33]
	v_mfma_f32_16x16x32_bf16 v[22:25], v[134:137], v[230:233], v[22:25]
	v_mfma_f32_16x16x32_bf16 v[14:17], v[142:145], v[230:233], v[14:17]
	s_setprio 0
	s_setprio 1
	v_mfma_f32_16x16x32_bf16 v[50:53], v[162:165], v[194:197], v[50:53]
	v_mfma_f32_16x16x32_bf16 v[42:45], v[170:173], v[194:197], v[42:45]
	v_mfma_f32_16x16x32_bf16 v[34:37], v[162:165], v[202:205], v[34:37]
	v_mfma_f32_16x16x32_bf16 v[26:29], v[170:173], v[202:205], v[26:29]
	v_mfma_f32_16x16x32_bf16 v[18:21], v[162:165], v[218:221], v[18:21]
	v_mfma_f32_16x16x32_bf16 v[10:13], v[170:173], v[218:221], v[10:13]
	v_mfma_f32_16x16x32_bf16 v[6:9], v[162:165], v[226:229], v[6:9]
	v_mfma_f32_16x16x32_bf16 v[2:5], v[170:173], v[226:229], v[2:5]
	v_mfma_f32_16x16x32_bf16 v[50:53], v[166:169], v[198:201], v[50:53]
	v_mfma_f32_16x16x32_bf16 v[42:45], v[190:193], v[198:201], v[42:45]
	v_mfma_f32_16x16x32_bf16 v[34:37], v[166:169], v[206:209], v[34:37]
	v_mfma_f32_16x16x32_bf16 v[26:29], v[190:193], v[206:209], v[26:29]
	v_mfma_f32_16x16x32_bf16 v[18:21], v[166:169], v[222:225], v[18:21]
	v_mfma_f32_16x16x32_bf16 v[10:13], v[190:193], v[222:225], v[10:13]
	v_mfma_f32_16x16x32_bf16 v[6:9], v[166:169], v[230:233], v[6:9]
	v_mfma_f32_16x16x32_bf16 v[2:5], v[190:193], v[230:233], v[2:5]
	s_setprio 0
	s_barrier
; #define PG8_STAGE(bufoff, gbase, voff) do { _Pragma("unroll") for (int _i = 0; _i < 2; ++_i) \
;         __builtin_amdgcn_global_load_lds((const unsigned*)((const char*)(gbase) + (voff)[_i]), (LAS unsigned*)(lds + (bufoff) + ldsw + _i * 8192), 16, 0, 0); } while (0)
; #define PG8_LDA(dst, b, h) do { _Pragma("unroll") for (int m = 0; m < 4; ++m) _Pragma("unroll") for (int k = 0; k < 2; ++k) dst[m][k] = *(const LAS bf16x8*)(lds + PG8_SA(b, h) + aoff + m * 2048 + k * 1024); } while (0)
; #define PG8_LDB(dst, b, h) do { _Pragma("unroll") for (int n = 0; n < 2; ++n) _Pragma("unroll") for (int k = 0; k < 2; ++k) dst[n][k] = *(const LAS bf16x8*)(lds + PG8_SB(b, h) + boff + n * 2048 + k * 1024); } while (0)
; #define PG8_MMA(ai, bj, At, Bt) do { __builtin_amdgcn_s_setprio(1); _Pragma("unroll") for (int m = 0; m < 4; ++m) _Pragma("unroll") for (int n = 0; n < 2; ++n) _Pragma("unroll") for (int k = 0; k < 2; ++k) \
;         acc[ai][bj][m][n] = __builtin_amdgcn_mfma_f32_16x16x32_bf16(Bt[n][k], At[m][k], acc[ai][bj][m][n], 0, 0, 0); __builtin_amdgcn_s_setprio(0); } while (0)
; #define PG8_WAIT_V(n) asm volatile("s_waitcnt vmcnt(" #n ")" ::: "memory")
; #define PG8_WAIT_L(n) asm volatile("s_waitcnt lgkmcnt(" #n ")" ::: "memory")
; #define PG8_BAR __builtin_amdgcn_s_barrier()
; #define PG8_SCHED __builtin_amdgcn_sched_barrier(0)
; template <class Epi, class Sched>
; __device__ __forceinline__ void gemm_phase(LAS unsigned char* lds, const Gemm g, const Sched& S, const Epi& E) {
;     ...
;             PG8_LDB(B0, 1, 0); PG8_LDB(B1, 1, 1); PG8_SCHED; PG8_LDA(At, 1, 0); PG8_STAGE(PG8_SA(0, 1), a2 + hstepA, voffA);
;             PG8_WAIT_V(8); PG8_WAIT_L(0); PG8_BAR; PG8_MMA(0, 0, At, B0); PG8_MMA(0, 1, At, B1); PG8_BAR; PG8_SCHED;
;             PG8_LDA(At, 1, 1); PG8_STAGE(PG8_SB(1, 0), b3, voffB); PG8_STAGE(PG8_SB(1, 1), b3 + hstepB, voffB); PG8_STAGE(PG8_SA(1, 0), a3, voffA);
;             PG8_WAIT_V(8); PG8_WAIT_L(0); PG8_BAR; PG8_MMA(1, 0, At, B0); PG8_MMA(1, 1, At, B1); PG8_BAR; PG8_SCHED;
;         }
	s_add_i32 s79, 0, 0x18000
	s_add_i32 s80, 0, 0x1c000
	ds_read_b128 v[130:133], v255 offset:32768
	ds_read_b128 v[134:137], v255 offset:33792
	ds_read_b128 v[138:141], v255 offset:34816
	ds_read_b128 v[142:145], v255 offset:35840
	ds_read_b128 v[162:165], v255 offset:49152
	ds_read_b128 v[166:169], v255 offset:50176
	ds_read_b128 v[170:173], v255 offset:51200
	ds_read_b128 v[190:193], v255 offset:52224
	s_add_u32 s20, s20, 0x40000
	s_addc_u32 s21, s21, 0
	s_mov_b32 m0, s29
	ds_read_b128 v[194:197], v160 offset:32768
	ds_read_b128 v[198:201], v160 offset:33792
	ds_read_b128 v[202:205], v160 offset:34816
	ds_read_b128 v[206:209], v160 offset:35840
	ds_read_b128 v[218:221], v160 offset:36864
	ds_read_b128 v[222:225], v160 offset:37888
	ds_read_b128 v[226:229], v160 offset:38912
	ds_read_b128 v[230:233], v160 offset:39936
	global_load_lds_dwordx4 v146, s[20:21]
	s_mov_b32 m0, s30
	s_nop 0
	global_load_lds_dwordx4 v150, s[20:21]
	s_waitcnt vmcnt(8)
	s_waitcnt lgkmcnt(0)
	s_barrier
	s_setprio 1
	s_waitcnt lgkmcnt(0)
	v_mfma_f32_16x16x32_bf16 v[126:129], v[130:133], v[194:197], v[126:129]
	v_mfma_f32_16x16x32_bf16 v[122:125], v[138:141], v[194:197], v[122:125]
	v_mfma_f32_16x16x32_bf16 v[118:121], v[130:133], v[202:205], v[118:121]
	v_mfma_f32_16x16x32_bf16 v[110:113], v[138:141], v[202:205], v[110:113]
	v_mfma_f32_16x16x32_bf16 v[102:105], v[130:133], v[218:221], v[102:105]
	v_mfma_f32_16x16x32_bf16 v[94:97], v[138:141], v[218:221], v[94:97]
	v_mfma_f32_16x16x32_bf16 v[86:89], v[130:133], v[226:229], v[86:89]
	v_mfma_f32_16x16x32_bf16 v[78:81], v[138:141], v[226:229], v[78:81]
	v_mfma_f32_16x16x32_bf16 v[126:129], v[134:137], v[198:201], v[126:129]
	v_mfma_f32_16x16x32_bf16 v[122:125], v[142:145], v[198:201], v[122:125]
	v_mfma_f32_16x16x32_bf16 v[118:121], v[134:137], v[206:209], v[118:121]
	v_mfma_f32_16x16x32_bf16 v[110:113], v[142:145], v[206:209], v[110:113]
	v_mfma_f32_16x16x32_bf16 v[102:105], v[134:137], v[222:225], v[102:105]
	v_mfma_f32_16x16x32_bf16 v[94:97], v[142:145], v[222:225], v[94:97]
	v_mfma_f32_16x16x32_bf16 v[86:89], v[134:137], v[230:233], v[86:89]
	v_mfma_f32_16x16x32_bf16 v[78:81], v[142:145], v[230:233], v[78:81]
	s_setprio 0
	s_setprio 1
	v_mfma_f32_16x16x32_bf16 v[114:117], v[162:165], v[194:197], v[114:117]
	v_mfma_f32_16x16x32_bf16 v[106:109], v[170:173], v[194:197], v[106:109]
	v_mfma_f32_16x16x32_bf16 v[98:101], v[162:165], v[202:205], v[98:101]
	v_mfma_f32_16x16x32_bf16 v[90:93], v[170:173], v[202:205], v[90:93]
	v_mfma_f32_16x16x32_bf16 v[82:85], v[162:165], v[218:221], v[82:85]
	v_mfma_f32_16x16x32_bf16 v[74:77], v[170:173], v[218:221], v[74:77]
	v_mfma_f32_16x16x32_bf16 v[70:73], v[162:165], v[226:229], v[70:73]
	v_mfma_f32_16x16x32_bf16 v[66:69], v[170:173], v[226:229], v[66:69]
	v_mfma_f32_16x16x32_bf16 v[114:117], v[166:169], v[198:201], v[114:117]
	v_mfma_f32_16x16x32_bf16 v[106:109], v[190:193], v[198:201], v[106:109]
	v_mfma_f32_16x16x32_bf16 v[98:101], v[166:169], v[206:209], v[98:101]
	v_mfma_f32_16x16x32_bf16 v[90:93], v[190:193], v[206:209], v[90:93]
	v_mfma_f32_16x16x32_bf16 v[82:85], v[166:169], v[222:225], v[82:85]
	v_mfma_f32_16x16x32_bf16 v[74:77], v[190:193], v[222:225], v[74:77]
	v_mfma_f32_16x16x32_bf16 v[70:73], v[166:169], v[230:233], v[70:73]
	v_mfma_f32_16x16x32_bf16 v[66:69], v[190:193], v[230:233], v[66:69]
	s_setprio 0
	s_barrier
	s_add_i32 s20, s8, 0x18000
	s_add_u32 s80, s76, 0x80
	s_addc_u32 s81, s77, 0
	s_mov_b32 m0, s20
	ds_read_b128 v[194:197], v160 offset:49152
	ds_read_b128 v[198:201], v160 offset:50176
	ds_read_b128 v[202:205], v160 offset:51200
	ds_read_b128 v[206:209], v160 offset:52224
	ds_read_b128 v[218:221], v160 offset:53248
	ds_read_b128 v[222:225], v160 offset:54272
	ds_read_b128 v[226:229], v160 offset:55296
	ds_read_b128 v[230:233], v160 offset:56320
	global_load_lds_dwordx4 v148, s[80:81]
	s_add_i32 m0, s20, 0x2000
	s_add_u32 s20, s76, 0x40080
	s_addc_u32 s21, s77, 0
	s_add_i32 s12, s8, 0x1c000
	global_load_lds_dwordx4 v152, s[80:81]
	s_mov_b32 m0, s12
	s_nop 0
	global_load_lds_dwordx4 v148, s[20:21]
	s_add_i32 m0, s12, 0x2000
	s_nop 0
	global_load_lds_dwordx4 v152, s[20:21]
	s_mov_b32 m0, s31
	s_nop 0
	global_load_lds_dwordx4 v146, s[100:101]
	s_mov_b32 m0, s34
	s_nop 0
	global_load_lds_dwordx4 v150, s[100:101]
	s_waitcnt vmcnt(8)
	s_waitcnt lgkmcnt(0)
	s_barrier
	s_setprio 1
	s_waitcnt lgkmcnt(0)
	v_mfma_f32_16x16x32_bf16 v[62:65], v[130:133], v[194:197], v[62:65]
	v_mfma_f32_16x16x32_bf16 v[58:61], v[138:141], v[194:197], v[58:61]
	v_mfma_f32_16x16x32_bf16 v[54:57], v[130:133], v[202:205], v[54:57]
	v_mfma_f32_16x16x32_bf16 v[46:49], v[138:141], v[202:205], v[46:49]
	v_mfma_f32_16x16x32_bf16 v[38:41], v[130:133], v[218:221], v[38:41]
	v_mfma_f32_16x16x32_bf16 v[30:33], v[138:141], v[218:221], v[30:33]
	v_mfma_f32_16x16x32_bf16 v[22:25], v[130:133], v[226:229], v[22:25]
	v_mfma_f32_16x16x32_bf16 v[14:17], v[138:141], v[226:229], v[14:17]
	v_mfma_f32_16x16x32_bf16 v[62:65], v[134:137], v[198:201], v[62:65]
	v_mfma_f32_16x16x32_bf16 v[58:61], v[142:145], v[198:201], v[58:61]
	v_mfma_f32_16x16x32_bf16 v[54:57], v[134:137], v[206:209], v[54:57]
	v_mfma_f32_16x16x32_bf16 v[46:49], v[142:145], v[206:209], v[46:49]
	v_mfma_f32_16x16x32_bf16 v[38:41], v[134:137], v[222:225], v[38:41]
	v_mfma_f32_16x16x32_bf16 v[30:33], v[142:145], v[222:225], v[30:33]
	v_mfma_f32_16x16x32_bf16 v[22:25], v[134:137], v[230:233], v[22:25]
	v_mfma_f32_16x16x32_bf16 v[14:17], v[142:145], v[230:233], v[14:17]
	s_setprio 0
	s_setprio 1
	v_mfma_f32_16x16x32_bf16 v[50:53], v[162:165], v[194:197], v[50:53]
	v_mfma_f32_16x16x32_bf16 v[42:45], v[170:173], v[194:197], v[42:45]
	v_mfma_f32_16x16x32_bf16 v[34:37], v[162:165], v[202:205], v[34:37]
	v_mfma_f32_16x16x32_bf16 v[26:29], v[170:173], v[202:205], v[26:29]
	v_mfma_f32_16x16x32_bf16 v[18:21], v[162:165], v[218:221], v[18:21]
	v_mfma_f32_16x16x32_bf16 v[10:13], v[170:173], v[218:221], v[10:13]
	v_mfma_f32_16x16x32_bf16 v[6:9], v[162:165], v[226:229], v[6:9]
	v_mfma_f32_16x16x32_bf16 v[2:5], v[170:173], v[226:229], v[2:5]
	v_mfma_f32_16x16x32_bf16 v[50:53], v[166:169], v[198:201], v[50:53]
	v_mfma_f32_16x16x32_bf16 v[42:45], v[190:193], v[198:201], v[42:45]
	v_mfma_f32_16x16x32_bf16 v[34:37], v[166:169], v[206:209], v[34:37]
	v_mfma_f32_16x16x32_bf16 v[26:29], v[190:193], v[206:209], v[26:29]
	v_mfma_f32_16x16x32_bf16 v[18:21], v[166:169], v[222:225], v[18:21]
	v_mfma_f32_16x16x32_bf16 v[10:13], v[190:193], v[222:225], v[10:13]
	v_mfma_f32_16x16x32_bf16 v[6:9], v[166:169], v[230:233], v[6:9]
	v_mfma_f32_16x16x32_bf16 v[2:5], v[190:193], v[230:233], v[2:5]
	s_setprio 0
	s_barrier
	s_add_i32 s78, s78, 2
	s_add_u32 s18, s18, 0x100
	s_addc_u32 s19, s19, 0
	s_add_u32 s69, s69, 0x100
	s_addc_u32 s71, s71, 0
	s_cmp_gt_u32 s78, 13
	s_cbranch_scc0 .LBB0_378
	s_and_b64 vcc, exec, s[36:37]
	s_cbranch_vccz .LBB0_381
	s_barrier

; #define PG8_STAGE(bufoff, gbase, voff) do { _Pragma("unroll") for (int _i = 0; _i < 2; ++_i) \
;         __builtin_amdgcn_global_load_lds((const unsigned*)((const char*)(gbase) + (voff)[_i]), (LAS unsigned*)(lds + (bufoff) + ldsw + _i * 8192), 16, 0, 0); } while (0)
; #define PG8_LDA(dst, b, h) do { _Pragma("unroll") for (int m = 0; m < 4; ++m) _Pragma("unroll") for (int k = 0; k < 2; ++k) dst[m][k] = *(const LAS bf16x8*)(lds + PG8_SA(b, h) + aoff + m * 2048 + k * 1024); } while (0)
; #define PG8_LDB(dst, b, h) do { _Pragma("unroll") for (int n = 0; n < 2; ++n) _Pragma("unroll") for (int k = 0; k < 2; ++k) dst[n][k] = *(const LAS bf16x8*)(lds + PG8_SB(b, h) + boff + n * 2048 + k * 1024); } while (0)
; #define PG8_MMA(ai, bj, At, Bt) do { __builtin_amdgcn_s_setprio(1); _Pragma("unroll") for (int m = 0; m < 4; ++m) _Pragma("unroll") for (int n = 0; n < 2; ++n) _Pragma("unroll") for (int k = 0; k < 2; ++k) \
;         acc[ai][bj][m][n] = __builtin_amdgcn_mfma_f32_16x16x32_bf16(Bt[n][k], At[m][k], acc[ai][bj][m][n], 0, 0, 0); __builtin_amdgcn_s_setprio(0); } while (0)
; #define PG8_WAIT_V(n) asm volatile("s_waitcnt vmcnt(" #n ")" ::: "memory")
; #define PG8_WAIT_L(n) asm volatile("s_waitcnt lgkmcnt(" #n ")" ::: "memory")
; #define PG8_BAR __builtin_amdgcn_s_barrier()
; #define PG8_SCHED __builtin_amdgcn_sched_barrier(0)
; template <class Epi, class Sched>
; __device__ __forceinline__ void gemm_phase(LAS unsigned char* lds, const Gemm g, const Sched& S, const Epi& E) {
;     ...
;         for (int t = 0; t < nt; t += 2) {
;             const bool last = (t == nt - 2);
;             const char* a1 = cA + (size_t)(t + 1) * kstep;
;             const char* a2 = last ? nA : cA + (size_t)(t + 2) * kstep; const char* b2 = last ? nB : cB + (size_t)(t + 2) * kstep;
;             const char* a3 = a2 + kstep; const char* b3 = b2 + kstep;
;             PG8_LDB(B0, 0, 0); PG8_LDB(B1, 0, 1); PG8_SCHED; PG8_LDA(At, 0, 0); PG8_STAGE(PG8_SA(1, 1), a1 + hstepA, voffA);
;             PG8_WAIT_V(8); PG8_WAIT_L(0); PG8_BAR; PG8_MMA(0, 0, At, B0); PG8_MMA(0, 1, At, B1); PG8_BAR; PG8_SCHED;
;             PG8_LDA(At, 0, 1); PG8_STAGE(PG8_SB(0, 0), b2, voffB); PG8_STAGE(PG8_SB(0, 1), b2 + hstepB, voffB); PG8_STAGE(PG8_SA(0, 0), a2, voffA);
;             PG8_WAIT_V(8); PG8_WAIT_L(0); PG8_BAR; PG8_MMA(1, 0, At, B0); PG8_MMA(1, 1, At, B1); PG8_BAR; PG8_SCHED;
.LBB0_639:
	s_add_u32 s18, s18, 0x80
	s_addc_u32 s19, s19, 0
	s_add_u32 s82, s82, 0x100
	s_addc_u32 s83, s83, 0
	s_mov_b32 s20, 0
	v_add_u32_e32 v255, 0x10000, v142
.LBB0_640:
	s_add_i32 s87, s20, 2
	s_add_u32 s88, s18, 0x80
	s_addc_u32 s21, s19, 0
	s_add_i32 s90, 0, 0x10000
	s_cmp_eq_u32 s43, s20
	s_cselect_b32 s21, s69, s21
	s_cselect_b32 s20, s68, s88
	s_cselect_b32 s89, s81, s83
	s_cselect_b32 s88, s80, s82
	s_add_i32 s91, 0, 0x14000
	ds_read_b128 v[146:149], v255
	ds_read_b128 v[150:153], v255 offset:1024
	ds_read_b128 v[154:157], v255 offset:2048
	ds_read_b128 v[158:161], v255 offset:3072
	ds_read_b128 v[162:165], v255 offset:16384
	ds_read_b128 v[166:169], v255 offset:17408
	ds_read_b128 v[170:173], v255 offset:18432
	ds_read_b128 v[190:193], v255 offset:19456
	s_add_i32 m0, s30, 0xc000
	ds_read_b128 v[194:197], v144
	ds_read_b128 v[198:201], v144 offset:1024
	ds_read_b128 v[202:205], v144 offset:2048
	ds_read_b128 v[206:209], v144 offset:3072
	ds_read_b128 v[218:221], v144 offset:4096
	ds_read_b128 v[222:225], v144 offset:5120
	ds_read_b128 v[226:229], v144 offset:6144
	ds_read_b128 v[230:233], v144 offset:7168
	global_load_lds_dwordx4 v138, s[18:19]
	s_add_i32 m0, s30, 0xe000
	s_nop 0
	global_load_lds_dwordx4 v140, s[18:19]
	s_waitcnt vmcnt(8)
	s_waitcnt lgkmcnt(0)
	s_barrier
	s_setprio 1
	s_waitcnt lgkmcnt(0)
	v_mfma_f32_16x16x32_bf16 v[2:5], v[146:149], v[194:197], v[2:5]
	v_mfma_f32_16x16x32_bf16 v[6:9], v[154:157], v[194:197], v[6:9]
	v_mfma_f32_16x16x32_bf16 v[10:13], v[146:149], v[202:205], v[10:13]
	v_mfma_f32_16x16x32_bf16 v[14:17], v[154:157], v[202:205], v[14:17]
	v_mfma_f32_16x16x32_bf16 v[26:29], v[146:149], v[218:221], v[26:29]
	v_mfma_f32_16x16x32_bf16 v[30:33], v[154:157], v[218:221], v[30:33]
	v_mfma_f32_16x16x32_bf16 v[42:45], v[146:149], v[226:229], v[42:45]
	v_mfma_f32_16x16x32_bf16 v[46:49], v[154:157], v[226:229], v[46:49]
	v_mfma_f32_16x16x32_bf16 v[2:5], v[150:153], v[198:201], v[2:5]
	v_mfma_f32_16x16x32_bf16 v[6:9], v[158:161], v[198:201], v[6:9]
	v_mfma_f32_16x16x32_bf16 v[10:13], v[150:153], v[206:209], v[10:13]
	v_mfma_f32_16x16x32_bf16 v[14:17], v[158:161], v[206:209], v[14:17]
	v_mfma_f32_16x16x32_bf16 v[26:29], v[150:153], v[222:225], v[26:29]
	v_mfma_f32_16x16x32_bf16 v[30:33], v[158:161], v[222:225], v[30:33]
	v_mfma_f32_16x16x32_bf16 v[42:45], v[150:153], v[230:233], v[42:45]
	v_mfma_f32_16x16x32_bf16 v[46:49], v[158:161], v[230:233], v[46:49]
	s_setprio 0
	s_setprio 1
	v_mfma_f32_16x16x32_bf16 v[18:21], v[162:165], v[194:197], v[18:21]
	v_mfma_f32_16x16x32_bf16 v[22:25], v[170:173], v[194:197], v[22:25]
	v_mfma_f32_16x16x32_bf16 v[34:37], v[162:165], v[202:205], v[34:37]
	v_mfma_f32_16x16x32_bf16 v[38:41], v[170:173], v[202:205], v[38:41]
	v_mfma_f32_16x16x32_bf16 v[50:53], v[162:165], v[218:221], v[50:53]
	v_mfma_f32_16x16x32_bf16 v[54:57], v[170:173], v[218:221], v[54:57]
	v_mfma_f32_16x16x32_bf16 v[58:61], v[162:165], v[226:229], v[58:61]
	v_mfma_f32_16x16x32_bf16 v[66:69], v[170:173], v[226:229], v[66:69]
	v_mfma_f32_16x16x32_bf16 v[18:21], v[166:169], v[198:201], v[18:21]
	v_mfma_f32_16x16x32_bf16 v[22:25], v[190:193], v[198:201], v[22:25]
	v_mfma_f32_16x16x32_bf16 v[34:37], v[166:169], v[206:209], v[34:37]
	v_mfma_f32_16x16x32_bf16 v[38:41], v[190:193], v[206:209], v[38:41]
	v_mfma_f32_16x16x32_bf16 v[50:53], v[166:169], v[222:225], v[50:53]
	v_mfma_f32_16x16x32_bf16 v[54:57], v[190:193], v[222:225], v[54:57]
	v_mfma_f32_16x16x32_bf16 v[58:61], v[166:169], v[230:233], v[58:61]
	v_mfma_f32_16x16x32_bf16 v[66:69], v[190:193], v[230:233], v[66:69]
	s_setprio 0
	s_barrier
	s_add_i32 s90, s90, s29
	s_add_u32 s98, s88, 0x80
	s_addc_u32 s99, s89, 0
	s_add_u32 s100, s20, 0x80
	s_addc_u32 s101, s21, 0
	s_mov_b32 m0, s90
	ds_read_b128 v[194:197], v144 offset:16384
	ds_read_b128 v[198:201], v144 offset:17408
	ds_read_b128 v[202:205], v144 offset:18432
	ds_read_b128 v[206:209], v144 offset:19456
	ds_read_b128 v[218:221], v144 offset:20480
	ds_read_b128 v[222:225], v144 offset:21504
	ds_read_b128 v[226:229], v144 offset:22528
	ds_read_b128 v[230:233], v144 offset:23552
	global_load_lds_dwordx4 v132, s[88:89]
	s_add_i32 m0, s90, 0x2000
	s_add_i32 s90, s91, s29
	global_load_lds_dwordx4 v136, s[88:89]
	s_add_u32 s88, s88, s8
	s_addc_u32 s89, s89, 0
	s_mov_b32 m0, s90
	s_nop 0
	global_load_lds_dwordx4 v132, s[88:89]
	s_add_i32 m0, s90, 0x2000
	s_nop 0
	global_load_lds_dwordx4 v136, s[88:89]
	s_mov_b32 m0, s30
	s_nop 0
	global_load_lds_dwordx4 v130, s[20:21]
	s_mov_b32 m0, s31
	s_nop 0
	global_load_lds_dwordx4 v134, s[20:21]
	s_waitcnt vmcnt(8)
	s_waitcnt lgkmcnt(0)
	s_barrier
; #define PG8_STAGE(bufoff, gbase, voff) do { _Pragma("unroll") for (int _i = 0; _i < 2; ++_i) \
;         __builtin_amdgcn_global_load_lds((const unsigned*)((const char*)(gbase) + (voff)[_i]), (LAS unsigned*)(lds + (bufoff) + ldsw + _i * 8192), 16, 0, 0); } while (0)
; #define PG8_LDA(dst, b, h) do { _Pragma("unroll") for (int m = 0; m < 4; ++m) _Pragma("unroll") for (int k = 0; k < 2; ++k) dst[m][k] = *(const LAS bf16x8*)(lds + PG8_SA(b, h) + aoff + m * 2048 + k * 1024); } while (0)
; #define PG8_LDB(dst, b, h) do { _Pragma("unroll") for (int n = 0; n < 2; ++n) _Pragma("unroll") for (int k = 0; k < 2; ++k) dst[n][k] = *(const LAS bf16x8*)(lds + PG8_SB(b, h) + boff + n * 2048 + k * 1024); } while (0)
; #define PG8_MMA(ai, bj, At, Bt) do { __builtin_amdgcn_s_setprio(1); _Pragma("unroll") for (int m = 0; m < 4; ++m) _Pragma("unroll") for (int n = 0; n < 2; ++n) _Pragma("unroll") for (int k = 0; k < 2; ++k) \
;         acc[ai][bj][m][n] = __builtin_amdgcn_mfma_f32_16x16x32_bf16(Bt[n][k], At[m][k], acc[ai][bj][m][n], 0, 0, 0); __builtin_amdgcn_s_setprio(0); } while (0)
; #define PG8_WAIT_V(n) asm volatile("s_waitcnt vmcnt(" #n ")" ::: "memory")
; #define PG8_WAIT_L(n) asm volatile("s_waitcnt lgkmcnt(" #n ")" ::: "memory")
; #define PG8_BAR __builtin_amdgcn_s_barrier()
; #define PG8_SCHED __builtin_amdgcn_sched_barrier(0)
; template <class Epi, class Sched>
; __device__ __forceinline__ void gemm_phase(LAS unsigned char* lds, const Gemm g, const Sched& S, const Epi& E) {
;     ...
;             PG8_WAIT_V(8); PG8_WAIT_L(0); PG8_BAR; PG8_MMA(1, 0, At, B0); PG8_MMA(1, 1, At, B1); PG8_BAR; PG8_SCHED;
;             PG8_LDB(B0, 1, 0); PG8_LDB(B1, 1, 1); PG8_SCHED; PG8_LDA(At, 1, 0); PG8_STAGE(PG8_SA(0, 1), a2 + hstepA, voffA);
;             PG8_WAIT_V(8); PG8_WAIT_L(0); PG8_BAR; PG8_MMA(0, 0, At, B0); PG8_MMA(0, 1, At, B1); PG8_BAR; PG8_SCHED;
	s_setprio 1
	s_waitcnt lgkmcnt(0)
	v_mfma_f32_16x16x32_bf16 v[62:65], v[146:149], v[194:197], v[62:65]
	v_mfma_f32_16x16x32_bf16 v[70:73], v[154:157], v[194:197], v[70:73]
	v_mfma_f32_16x16x32_bf16 v[78:81], v[146:149], v[202:205], v[78:81]
	v_mfma_f32_16x16x32_bf16 v[82:85], v[154:157], v[202:205], v[82:85]
	v_mfma_f32_16x16x32_bf16 v[90:93], v[146:149], v[218:221], v[90:93]
	v_mfma_f32_16x16x32_bf16 v[94:97], v[154:157], v[218:221], v[94:97]
	v_mfma_f32_16x16x32_bf16 v[106:109], v[146:149], v[226:229], v[106:109]
	v_mfma_f32_16x16x32_bf16 v[110:113], v[154:157], v[226:229], v[110:113]
	v_mfma_f32_16x16x32_bf16 v[62:65], v[150:153], v[198:201], v[62:65]
	v_mfma_f32_16x16x32_bf16 v[70:73], v[158:161], v[198:201], v[70:73]
	v_mfma_f32_16x16x32_bf16 v[78:81], v[150:153], v[206:209], v[78:81]
	v_mfma_f32_16x16x32_bf16 v[82:85], v[158:161], v[206:209], v[82:85]
	v_mfma_f32_16x16x32_bf16 v[90:93], v[150:153], v[222:225], v[90:93]
	v_mfma_f32_16x16x32_bf16 v[94:97], v[158:161], v[222:225], v[94:97]
	v_mfma_f32_16x16x32_bf16 v[106:109], v[150:153], v[230:233], v[106:109]
	v_mfma_f32_16x16x32_bf16 v[110:113], v[158:161], v[230:233], v[110:113]
	s_setprio 0
	s_setprio 1
	v_mfma_f32_16x16x32_bf16 v[74:77], v[162:165], v[194:197], v[74:77]
	v_mfma_f32_16x16x32_bf16 v[86:89], v[170:173], v[194:197], v[86:89]
	v_mfma_f32_16x16x32_bf16 v[98:101], v[162:165], v[202:205], v[98:101]
	v_mfma_f32_16x16x32_bf16 v[102:105], v[170:173], v[202:205], v[102:105]
	v_mfma_f32_16x16x32_bf16 v[114:117], v[162:165], v[218:221], v[114:117]
	v_mfma_f32_16x16x32_bf16 v[118:121], v[170:173], v[218:221], v[118:121]
	v_mfma_f32_16x16x32_bf16 v[122:125], v[162:165], v[226:229], v[122:125]
	v_mfma_f32_16x16x32_bf16 v[126:129], v[170:173], v[226:229], v[126:129]
	v_mfma_f32_16x16x32_bf16 v[74:77], v[166:169], v[198:201], v[74:77]
	v_mfma_f32_16x16x32_bf16 v[86:89], v[190:193], v[198:201], v[86:89]
	v_mfma_f32_16x16x32_bf16 v[98:101], v[166:169], v[206:209], v[98:101]
	v_mfma_f32_16x16x32_bf16 v[102:105], v[190:193], v[206:209], v[102:105]
	v_mfma_f32_16x16x32_bf16 v[114:117], v[166:169], v[222:225], v[114:117]
	v_mfma_f32_16x16x32_bf16 v[118:121], v[190:193], v[222:225], v[118:121]
	v_mfma_f32_16x16x32_bf16 v[122:125], v[166:169], v[230:233], v[122:125]
	v_mfma_f32_16x16x32_bf16 v[126:129], v[190:193], v[230:233], v[126:129]
	s_setprio 0
	s_barrier
	ds_read_b128 v[146:149], v255 offset:32768
	ds_read_b128 v[150:153], v255 offset:33792
	ds_read_b128 v[154:157], v255 offset:34816
	ds_read_b128 v[158:161], v255 offset:35840
	ds_read_b128 v[162:165], v255 offset:49152
	ds_read_b128 v[166:169], v255 offset:50176
	ds_read_b128 v[170:173], v255 offset:51200
	ds_read_b128 v[190:193], v255 offset:52224
	s_add_u32 s20, s20, s54
	s_addc_u32 s21, s21, 0
	s_mov_b32 m0, s34
	ds_read_b128 v[194:197], v144 offset:32768
	ds_read_b128 v[198:201], v144 offset:33792
	ds_read_b128 v[202:205], v144 offset:34816
	ds_read_b128 v[206:209], v144 offset:35840
	ds_read_b128 v[218:221], v144 offset:36864
	ds_read_b128 v[222:225], v144 offset:37888
	ds_read_b128 v[226:229], v144 offset:38912
	ds_read_b128 v[230:233], v144 offset:39936
	global_load_lds_dwordx4 v130, s[20:21]
	s_mov_b32 m0, s35
	s_nop 0
	global_load_lds_dwordx4 v134, s[20:21]
	s_waitcnt vmcnt(8)
	s_waitcnt lgkmcnt(0)
	s_barrier
	s_setprio 1
	s_waitcnt lgkmcnt(0)
	v_mfma_f32_16x16x32_bf16 v[2:5], v[146:149], v[194:197], v[2:5]
	v_mfma_f32_16x16x32_bf16 v[6:9], v[154:157], v[194:197], v[6:9]
	v_mfma_f32_16x16x32_bf16 v[10:13], v[146:149], v[202:205], v[10:13]
	v_mfma_f32_16x16x32_bf16 v[14:17], v[154:157], v[202:205], v[14:17]
	v_mfma_f32_16x16x32_bf16 v[26:29], v[146:149], v[218:221], v[26:29]
	v_mfma_f32_16x16x32_bf16 v[30:33], v[154:157], v[218:221], v[30:33]
	v_mfma_f32_16x16x32_bf16 v[42:45], v[146:149], v[226:229], v[42:45]
	v_mfma_f32_16x16x32_bf16 v[46:49], v[154:157], v[226:229], v[46:49]
	v_mfma_f32_16x16x32_bf16 v[2:5], v[150:153], v[198:201], v[2:5]
	v_mfma_f32_16x16x32_bf16 v[6:9], v[158:161], v[198:201], v[6:9]
	v_mfma_f32_16x16x32_bf16 v[10:13], v[150:153], v[206:209], v[10:13]
	v_mfma_f32_16x16x32_bf16 v[14:17], v[158:161], v[206:209], v[14:17]
	v_mfma_f32_16x16x32_bf16 v[26:29], v[150:153], v[222:225], v[26:29]
	v_mfma_f32_16x16x32_bf16 v[30:33], v[158:161], v[222:225], v[30:33]
	v_mfma_f32_16x16x32_bf16 v[42:45], v[150:153], v[230:233], v[42:45]
	v_mfma_f32_16x16x32_bf16 v[46:49], v[158:161], v[230:233], v[46:49]
	s_setprio 0
	s_setprio 1
	v_mfma_f32_16x16x32_bf16 v[18:21], v[162:165], v[194:197], v[18:21]
	v_mfma_f32_16x16x32_bf16 v[22:25], v[170:173], v[194:197], v[22:25]
	v_mfma_f32_16x16x32_bf16 v[34:37], v[162:165], v[202:205], v[34:37]
	v_mfma_f32_16x16x32_bf16 v[38:41], v[170:173], v[202:205], v[38:41]
	v_mfma_f32_16x16x32_bf16 v[50:53], v[162:165], v[218:221], v[50:53]
	v_mfma_f32_16x16x32_bf16 v[54:57], v[170:173], v[218:221], v[54:57]
	v_mfma_f32_16x16x32_bf16 v[58:61], v[162:165], v[226:229], v[58:61]
	v_mfma_f32_16x16x32_bf16 v[66:69], v[170:173], v[226:229], v[66:69]
	v_mfma_f32_16x16x32_bf16 v[18:21], v[166:169], v[198:201], v[18:21]
	v_mfma_f32_16x16x32_bf16 v[22:25], v[190:193], v[198:201], v[22:25]
	v_mfma_f32_16x16x32_bf16 v[34:37], v[166:169], v[206:209], v[34:37]
	v_mfma_f32_16x16x32_bf16 v[38:41], v[190:193], v[206:209], v[38:41]
	v_mfma_f32_16x16x32_bf16 v[50:53], v[166:169], v[222:225], v[50:53]
	v_mfma_f32_16x16x32_bf16 v[54:57], v[190:193], v[222:225], v[54:57]
	v_mfma_f32_16x16x32_bf16 v[58:61], v[166:169], v[230:233], v[58:61]
	v_mfma_f32_16x16x32_bf16 v[66:69], v[190:193], v[230:233], v[66:69]
	s_setprio 0
	s_barrier
; #define PG8_STAGE(bufoff, gbase, voff) do { _Pragma("unroll") for (int _i = 0; _i < 2; ++_i) \
;         __builtin_amdgcn_global_load_lds((const unsigned*)((const char*)(gbase) + (voff)[_i]), (LAS unsigned*)(lds + (bufoff) + ldsw + _i * 8192), 16, 0, 0); } while (0)
; #define PG8_LDA(dst, b, h) do { _Pragma("unroll") for (int m = 0; m < 4; ++m) _Pragma("unroll") for (int k = 0; k < 2; ++k) dst[m][k] = *(const LAS bf16x8*)(lds + PG8_SA(b, h) + aoff + m * 2048 + k * 1024); } while (0)
; #define PG8_MMA(ai, bj, At, Bt) do { __builtin_amdgcn_s_setprio(1); _Pragma("unroll") for (int m = 0; m < 4; ++m) _Pragma("unroll") for (int n = 0; n < 2; ++n) _Pragma("unroll") for (int k = 0; k < 2; ++k) \
;         acc[ai][bj][m][n] = __builtin_amdgcn_mfma_f32_16x16x32_bf16(Bt[n][k], At[m][k], acc[ai][bj][m][n], 0, 0, 0); __builtin_amdgcn_s_setprio(0); } while (0)
; #define PG8_WAIT_V(n) asm volatile("s_waitcnt vmcnt(" #n ")" ::: "memory")
; #define PG8_WAIT_L(n) asm volatile("s_waitcnt lgkmcnt(" #n ")" ::: "memory")
; #define PG8_BAR __builtin_amdgcn_s_barrier()
; #define PG8_SCHED __builtin_amdgcn_sched_barrier(0)
; template <class Epi, class Sched>
; __device__ __forceinline__ void gemm_phase(LAS unsigned char* lds, const Gemm g, const Sched& S, const Epi& E) {
;     ...
;             PG8_LDA(At, 1, 1); PG8_STAGE(PG8_SB(1, 0), b3, voffB); PG8_STAGE(PG8_SB(1, 1), b3 + hstepB, voffB); PG8_STAGE(PG8_SA(1, 0), a3, voffA);
;             PG8_WAIT_V(8); PG8_WAIT_L(0); PG8_BAR; PG8_MMA(1, 0, At, B0); PG8_MMA(1, 1, At, B1); PG8_BAR; PG8_SCHED;
;         }
	s_add_i32 s20, s29, 0x18000
	s_mov_b32 m0, s20
	ds_read_b128 v[194:197], v144 offset:49152
	ds_read_b128 v[198:201], v144 offset:50176
	ds_read_b128 v[202:205], v144 offset:51200
	ds_read_b128 v[206:209], v144 offset:52224
	ds_read_b128 v[218:221], v144 offset:53248
	ds_read_b128 v[222:225], v144 offset:54272
	ds_read_b128 v[226:229], v144 offset:55296
	ds_read_b128 v[230:233], v144 offset:56320
	global_load_lds_dwordx4 v132, s[98:99]
	s_add_i32 m0, s20, 0x2000
	s_add_i32 s20, s29, 0x1c000
	global_load_lds_dwordx4 v136, s[98:99]
	s_add_u32 s98, s98, s8
	s_addc_u32 s99, s99, 0
	s_mov_b32 m0, s20
	s_nop 0
	global_load_lds_dwordx4 v132, s[98:99]
	s_add_i32 m0, s20, 0x2000
	s_nop 0
	global_load_lds_dwordx4 v136, s[98:99]
	s_mov_b32 m0, s40
	s_nop 0
	global_load_lds_dwordx4 v130, s[100:101]
	s_mov_b32 m0, s41
	s_nop 0
	global_load_lds_dwordx4 v134, s[100:101]
	s_waitcnt vmcnt(8)
	s_waitcnt lgkmcnt(0)
	s_barrier
	s_setprio 1
	s_waitcnt lgkmcnt(0)
	v_mfma_f32_16x16x32_bf16 v[62:65], v[146:149], v[194:197], v[62:65]
	v_mfma_f32_16x16x32_bf16 v[70:73], v[154:157], v[194:197], v[70:73]
	v_mfma_f32_16x16x32_bf16 v[78:81], v[146:149], v[202:205], v[78:81]
	v_mfma_f32_16x16x32_bf16 v[82:85], v[154:157], v[202:205], v[82:85]
	v_mfma_f32_16x16x32_bf16 v[90:93], v[146:149], v[218:221], v[90:93]
	v_mfma_f32_16x16x32_bf16 v[94:97], v[154:157], v[218:221], v[94:97]
	v_mfma_f32_16x16x32_bf16 v[106:109], v[146:149], v[226:229], v[106:109]
	v_mfma_f32_16x16x32_bf16 v[110:113], v[154:157], v[226:229], v[110:113]
	v_mfma_f32_16x16x32_bf16 v[62:65], v[150:153], v[198:201], v[62:65]
	v_mfma_f32_16x16x32_bf16 v[70:73], v[158:161], v[198:201], v[70:73]
	v_mfma_f32_16x16x32_bf16 v[78:81], v[150:153], v[206:209], v[78:81]
	v_mfma_f32_16x16x32_bf16 v[82:85], v[158:161], v[206:209], v[82:85]
	v_mfma_f32_16x16x32_bf16 v[90:93], v[150:153], v[222:225], v[90:93]
	v_mfma_f32_16x16x32_bf16 v[94:97], v[158:161], v[222:225], v[94:97]
	v_mfma_f32_16x16x32_bf16 v[106:109], v[150:153], v[230:233], v[106:109]
	v_mfma_f32_16x16x32_bf16 v[110:113], v[158:161], v[230:233], v[110:113]
	s_setprio 0
	s_setprio 1
	v_mfma_f32_16x16x32_bf16 v[74:77], v[162:165], v[194:197], v[74:77]
	v_mfma_f32_16x16x32_bf16 v[86:89], v[170:173], v[194:197], v[86:89]
	v_mfma_f32_16x16x32_bf16 v[98:101], v[162:165], v[202:205], v[98:101]
	v_mfma_f32_16x16x32_bf16 v[102:105], v[170:173], v[202:205], v[102:105]
	v_mfma_f32_16x16x32_bf16 v[114:117], v[162:165], v[218:221], v[114:117]
	v_mfma_f32_16x16x32_bf16 v[118:121], v[170:173], v[218:221], v[118:121]
	v_mfma_f32_16x16x32_bf16 v[122:125], v[162:165], v[226:229], v[122:125]
	v_mfma_f32_16x16x32_bf16 v[126:129], v[170:173], v[226:229], v[126:129]
	v_mfma_f32_16x16x32_bf16 v[74:77], v[166:169], v[198:201], v[74:77]
	v_mfma_f32_16x16x32_bf16 v[86:89], v[190:193], v[198:201], v[86:89]
	v_mfma_f32_16x16x32_bf16 v[98:101], v[166:169], v[206:209], v[98:101]
	v_mfma_f32_16x16x32_bf16 v[102:105], v[190:193], v[206:209], v[102:105]
	v_mfma_f32_16x16x32_bf16 v[114:117], v[166:169], v[222:225], v[114:117]
	v_mfma_f32_16x16x32_bf16 v[118:121], v[190:193], v[222:225], v[118:121]
	v_mfma_f32_16x16x32_bf16 v[122:125], v[166:169], v[230:233], v[122:125]
	v_mfma_f32_16x16x32_bf16 v[126:129], v[190:193], v[230:233], v[126:129]
	s_setprio 0
	s_barrier
	s_add_u32 s18, s18, 0x100
	s_addc_u32 s19, s19, 0
	s_add_u32 s82, s82, 0x100
	s_addc_u32 s83, s83, 0
	s_cmp_ge_u32 s87, s42
	s_mov_b32 s20, s87
	s_cbranch_scc0 .LBB0_640
	s_and_b64 vcc, exec, s[70:71]
	s_cbranch_vccz .LBB0_643
	s_barrier
